# v62 + P5 sample tiles: x_sample residual loads issued right after the small GEMM's last operand loads (overlap the HBM round trip with the GEMM + reduce)
# baseline (speedup 1.0000x reference)
; #define LAS __attribute__((address_space(3)))
; template <int KSTEPS  >
; __device__ __forceinline__ void small_gemm_tile(Frame& F, const bf16* A, int lda, const bf16* Bt, int K, int r0, int c0, float (&v)[8]) {
;     ...
;     const bf16* ap = A + (size_t)(r0 + lr) * lda + wave * (KSTEPS * 32) + 8 * lp;
;     const bf16* bp = Bt + (size_t)(c0 + lr) * K + wave * (KSTEPS * 32) + 8 * lp;
;     LAS unsigned char* SWA = F.lds + wave * 10240; LAS unsigned char* SWB = SWA + 5120;
;     v4u ra[D][4], rb[D][4];
; #pragma unroll
;     for (int s = 0; s < D - 1; ++s)
; #pragma unroll
;         for (int i = 0; i < 4; ++i) { ra[s][i] = *(const v4u*)(ap + (size_t)(16 * i) * lda + 32 * s); rb[s][i] = *(const v4u*)(bp + (size_t)(16 * i) * K + 32 * s); }
; #pragma unroll
;     for (int s = 0; s < KSTEPS; ++s) {
;         if (s + D - 1 < KSTEPS) {
; #pragma unroll
;             for (int i = 0; i < 4; ++i) { ra[(s + D - 1) % D][i] = *(const v4u*)(ap + (size_t)(16 * i) * lda + 32 * (s + D - 1)); rb[(s + D - 1) % D][i] = *(const v4u*)(bp + (size_t)(16 * i) * K + 32 * (s + D - 1)); } }
; #pragma unroll
;         for (int i = 0; i < 4; ++i) { *(LAS v4u*)(SWA + (16 * i + lr) * 80 + lp * 16) = ra[s % D][i]; *(LAS v4u*)(SWB + (16 * i + lr) * 80 + lp * 16) = rb[s % D][i]; }
;         s16x8 af[4], bf[4];
; #pragma unroll
;         for (int i = 0; i < 4; ++i) { af[i] = *(const LAS s16x8*)(SWA + (16 * i + fr) * 80 + fq * 16); bf[i] = *(const LAS s16x8*)(SWB + (16 * i + fr) * 80 + fq * 16); }
; #pragma unroll
;         for (int a = 0; a < 4; ++a)
; #pragma unroll
;             for (int bb = 0; bb < 4; ++bb) acc[a][bb] = __builtin_amdgcn_mfma_f32_16x16x32_bf16(bf[bb], af[a], acc[a][bb], 0, 0, 0);
.LBB0_760:
.LBB0_761:
	s_lshl_b32 s1, s2, 2
	s_andn2_b32 s1, s1, 63
	s_add_i32 s0, s1, 0x4000
	v_lshrrev_b32_e32 v36, 2, v154
	v_or_b32_e32 v2, s0, v36
	v_ashrrev_i32_e32 v3, 31, v2
	v_lshlrev_b64 v[2:3], 11, v[2:3]
	s_lshl_b32 s3, s2, 6
	v_and_b32_e32 v6, 3, v0
	v_lshl_add_u64 v[2:3], s[8:9], 0, v[2:3]
	s_lshl_b32 s4, s96, 8
	s_mov_b32 s5, 0
	s_and_b32 s3, s3, 0x380
	v_lshl_add_u64 v[4:5], v[2:3], 0, s[4:5]
	v_lshlrev_b32_e32 v2, 4, v6
	v_mov_b32_e32 v3, 0
	v_lshl_add_u64 v[120:121], v[4:5], 0, v[2:3]
	v_or_b32_e32 v4, s3, v36
	v_lshlrev_b32_e32 v4, 11, v4
	v_mov_b32_e32 v5, v3
	v_lshl_add_u64 v[4:5], s[14:15], 0, v[4:5]
	v_lshl_add_u64 v[4:5], v[4:5], 0, s[4:5]
	s_mov_b32 s4, 0x8000
	v_add_co_u32_e32 v128, vcc, s4, v120
	v_lshl_add_u64 v[124:125], v[4:5], 0, v[2:3]
	s_nop 0
	v_addc_co_u32_e32 v129, vcc, 0, v121, vcc
	v_add_co_u32_e32 v130, vcc, s4, v124
	s_mov_b32 s4, 0x10000
	s_nop 0
	v_addc_co_u32_e32 v131, vcc, 0, v125, vcc
	v_add_co_u32_e32 v132, vcc, s4, v120
	global_load_dwordx4 v[4:7], v[120:121], off
	global_load_dwordx4 v[8:11], v[124:125], off
	v_addc_co_u32_e32 v133, vcc, 0, v121, vcc
	v_add_co_u32_e32 v136, vcc, s4, v124
	s_mov_b32 s4, 0x18000
	s_nop 0
	v_addc_co_u32_e32 v137, vcc, 0, v125, vcc
	v_add_co_u32_e32 v140, vcc, s4, v124
	global_load_dwordx4 v[12:15], v[128:129], off
	global_load_dwordx4 v[16:19], v[130:131], off
	v_addc_co_u32_e32 v141, vcc, 0, v125, vcc
	global_load_dwordx4 v[20:23], v[132:133], off
	global_load_dwordx4 v[24:27], v[136:137], off
	v_add_co_u32_e32 v138, vcc, s4, v120
	s_mul_i32 s4, s96, 0x2800
	v_and_b32_e32 v167, 15, v0
	global_load_dwordx4 v[28:31], v[140:141], off
	v_addc_co_u32_e32 v139, vcc, 0, v121, vcc
	v_and_b32_e32 v144, 48, v0
	s_add_i32 s4, s4, 0
	v_mul_u32_u24_e32 v36, 0x50, v36
	v_mul_u32_u24_e32 v37, 0x50, v167
	global_load_dwordx4 v[32:35], v[138:139], off
	v_add3_u32 v2, s4, v2, v36
	v_add3_u32 v145, s4, v144, v37
	global_load_dwordx4 v[36:39], v[124:125], off offset:64
	global_load_dwordx4 v[40:43], v[130:131], off offset:64
	global_load_dwordx4 v[44:47], v[136:137], off offset:64
	global_load_dwordx4 v[48:51], v[140:141], off offset:64
	global_load_dwordx4 v[52:55], v[120:121], off offset:64
	global_load_dwordx4 v[56:59], v[128:129], off offset:64
	global_load_dwordx4 v[60:63], v[132:133], off offset:64
	global_load_dwordx4 v[64:67], v[138:139], off offset:64
	s_mul_i32 s4, s96, 0x4400
	s_add_i32 s4, s4, 0
	v_lshrrev_b32_e32 v155, 3, v0
	v_readlane_b32 s60, v238, 4
	v_readlane_b32 s62, v238, 6
	v_readlane_b32 s63, v238, 7
	v_readlane_b32 s61, v238, 5
	v_readlane_b32 s64, v238, 8
	v_readlane_b32 s65, v238, 9
	v_readlane_b32 s66, v238, 10
	v_readlane_b32 s67, v238, 11
	v_readlane_b32 s68, v238, 12
	v_readlane_b32 s69, v238, 13
	v_readlane_b32 s70, v238, 14
	v_readlane_b32 s71, v238, 15
	v_readlane_b32 s72, v238, 16
	v_readlane_b32 s73, v238, 17
	v_readlane_b32 s74, v238, 18
	v_readlane_b32 s75, v238, 19
	s_waitcnt vmcnt(0)
	ds_write_b128 v2, v[8:11] offset:5120
	ds_write_b128 v2, v[16:19] offset:6400
	ds_write_b128 v2, v[24:27] offset:7680
	ds_write_b128 v2, v[28:31] offset:8960
	ds_write_b128 v2, v[4:7]
	ds_write_b128 v2, v[12:15] offset:1280
	ds_write_b128 v2, v[20:23] offset:2560
	ds_write_b128 v2, v[32:35] offset:3840
	ds_read_b128 v[4:7], v145 offset:5120
	ds_read_b128 v[8:11], v145 offset:6400
	ds_read_b128 v[12:15], v145
	ds_read_b128 v[16:19], v145 offset:1280
	ds_read_b128 v[24:27], v145 offset:7680
	ds_read_b128 v[32:35], v145 offset:8960
	ds_read_b128 v[84:87], v145 offset:2560
	ds_read_b128 v[88:91], v145 offset:3840
	ds_write_b128 v2, v[52:55]
	ds_write_b128 v2, v[36:39] offset:5120
	ds_write_b128 v2, v[56:59] offset:1280
	ds_write_b128 v2, v[40:43] offset:6400
	ds_write_b128 v2, v[60:63] offset:2560
	ds_write_b128 v2, v[44:47] offset:7680
	ds_write_b128 v2, v[64:67] offset:3840
	ds_write_b128 v2, v[48:51] offset:8960
	ds_read_b128 v[36:39], v145 offset:5120
	ds_read_b128 v[40:43], v145 offset:6400
	ds_read_b128 v[44:47], v145
	ds_read_b128 v[48:51], v145 offset:1280
	ds_read_b128 v[52:55], v145 offset:7680
	ds_read_b128 v[56:59], v145 offset:8960
	s_waitcnt lgkmcnt(14)
	v_mfma_f32_16x16x32_bf16 v[20:23], v[4:7], v[12:15], 0
	v_mfma_f32_16x16x32_bf16 v[28:31], v[8:11], v[12:15], 0
	v_mfma_f32_16x16x32_bf16 v[68:71], v[24:27], v[12:15], 0
	v_mfma_f32_16x16x32_bf16 v[12:15], v[32:35], v[12:15], 0
	v_mfma_f32_16x16x32_bf16 v[72:75], v[4:7], v[16:19], 0
	v_mfma_f32_16x16x32_bf16 v[76:79], v[8:11], v[16:19], 0
	v_mfma_f32_16x16x32_bf16 v[80:83], v[24:27], v[16:19], 0
	v_mfma_f32_16x16x32_bf16 v[16:19], v[32:35], v[16:19], 0
	v_mfma_f32_16x16x32_bf16 v[92:95], v[4:7], v[84:87], 0
	v_mfma_f32_16x16x32_bf16 v[96:99], v[8:11], v[84:87], 0
	s_waitcnt lgkmcnt(3)
	v_mfma_f32_16x16x32_bf16 v[20:23], v[36:39], v[44:47], v[20:23]
	v_mfma_f32_16x16x32_bf16 v[28:31], v[40:43], v[44:47], v[28:31]
	s_waitcnt lgkmcnt(1)
	v_mfma_f32_16x16x32_bf16 v[60:63], v[52:55], v[44:47], v[68:71]
	s_waitcnt lgkmcnt(0)
	v_mfma_f32_16x16x32_bf16 v[12:15], v[56:59], v[44:47], v[12:15]
	v_mfma_f32_16x16x32_bf16 v[44:47], v[36:39], v[48:51], v[72:75]
	v_mfma_f32_16x16x32_bf16 v[64:67], v[40:43], v[48:51], v[76:79]
	v_mfma_f32_16x16x32_bf16 v[68:71], v[52:55], v[48:51], v[80:83]
	v_mfma_f32_16x16x32_bf16 v[16:19], v[56:59], v[48:51], v[16:19]
	ds_read_b128 v[48:51], v145 offset:2560
	ds_read_b128 v[72:75], v145 offset:3840
	global_load_dwordx4 v[80:83], v[120:121], off offset:128
	v_mfma_f32_16x16x32_bf16 v[100:103], v[24:27], v[84:87], 0
	v_mfma_f32_16x16x32_bf16 v[84:87], v[32:35], v[84:87], 0
	v_mfma_f32_16x16x32_bf16 v[4:7], v[4:7], v[88:91], 0
	v_mfma_f32_16x16x32_bf16 v[8:11], v[8:11], v[88:91], 0
	v_mfma_f32_16x16x32_bf16 v[24:27], v[24:27], v[88:91], 0
	v_mfma_f32_16x16x32_bf16 v[32:35], v[32:35], v[88:91], 0
	s_waitcnt lgkmcnt(1)
; #define LAS __attribute__((address_space(3)))
; template <int KSTEPS  >
; __device__ __forceinline__ void small_gemm_tile(Frame& F, const bf16* A, int lda, const bf16* Bt, int K, int r0, int c0, float (&v)[8]) {
;     ...
;     for (int s = 0; s < KSTEPS; ++s) {
;         if (s + D - 1 < KSTEPS) {
; #pragma unroll
;             for (int i = 0; i < 4; ++i) { ra[(s + D - 1) % D][i] = *(const v4u*)(ap + (size_t)(16 * i) * lda + 32 * (s + D - 1)); rb[(s + D - 1) % D][i] = *(const v4u*)(bp + (size_t)(16 * i) * K + 32 * (s + D - 1)); } }
; #pragma unroll
;         for (int i = 0; i < 4; ++i) { *(LAS v4u*)(SWA + (16 * i + lr) * 80 + lp * 16) = ra[s % D][i]; *(LAS v4u*)(SWB + (16 * i + lr) * 80 + lp * 16) = rb[s % D][i]; }
;         s16x8 af[4], bf[4];
; #pragma unroll
;         for (int i = 0; i < 4; ++i) { af[i] = *(const LAS s16x8*)(SWA + (16 * i + fr) * 80 + fq * 16); bf[i] = *(const LAS s16x8*)(SWB + (16 * i + fr) * 80 + fq * 16); }
; #pragma unroll
;         for (int a = 0; a < 4; ++a)
; #pragma unroll
;             for (int bb = 0; bb < 4; ++bb) acc[a][bb] = __builtin_amdgcn_mfma_f32_16x16x32_bf16(bf[bb], af[a], acc[a][bb], 0, 0, 0);
;     }
; __device__ __forceinline__ void outproj_sample_tile(Frame& F, int tile, float* SS1) {
;     ...
;     const float* xs = F.in[1] + (size_t)(row - MP) * DM + col; bf16* XN = (bf16*)(F.ws + WS_XN);
;     const f32x4v xa = *(const f32x4v*)xs, xb = *(const f32x4v*)(xs + 4);
	v_mfma_f32_16x16x32_bf16 v[76:79], v[36:39], v[48:51], v[92:95]
	v_mfma_f32_16x16x32_bf16 v[88:91], v[40:43], v[48:51], v[96:99]
	s_nop 1
	global_load_dwordx4 v[92:95], v[124:125], off offset:128
	global_load_dwordx4 v[96:99], v[128:129], off offset:128
	global_load_dwordx4 v[104:107], v[130:131], off offset:128
	global_load_dwordx4 v[108:111], v[132:133], off offset:128
	global_load_dwordx4 v[112:115], v[136:137], off offset:128
	global_load_dwordx4 v[116:119], v[138:139], off offset:128
	v_mfma_f32_16x16x32_bf16 v[100:103], v[52:55], v[48:51], v[100:103]
	v_mfma_f32_16x16x32_bf16 v[48:51], v[56:59], v[48:51], v[84:87]
	s_nop 2
	global_load_dwordx4 v[84:87], v[140:141], off offset:128
	s_nop 0
	global_load_dwordx4 v[120:123], v[120:121], off offset:192
	s_nop 0
	global_load_dwordx4 v[124:127], v[124:125], off offset:192
	s_waitcnt lgkmcnt(0)
	v_mfma_f32_16x16x32_bf16 v[4:7], v[36:39], v[72:75], v[4:7]
	global_load_dwordx4 v[36:39], v[128:129], off offset:192
	s_nop 0
	global_load_dwordx4 v[128:131], v[130:131], off offset:192
	s_nop 0
	global_load_dwordx4 v[132:135], v[132:133], off offset:192
	v_mfma_f32_16x16x32_bf16 v[8:11], v[40:43], v[72:75], v[8:11]
	global_load_dwordx4 v[40:43], v[136:137], off offset:192
	s_nop 0
	global_load_dwordx4 v[136:139], v[138:139], off offset:192
	s_nop 0
	global_load_dwordx4 v[140:143], v[140:141], off offset:192
	v_or_b32_e32 v224, s1, v155
	v_mov_b32_e32 v225, 0
	v_lshlrev_b64 v[224:225], 12, v[224:225]
	v_lshl_add_u64 v[224:225], s[62:63], 0, v[224:225]
	v_lshlrev_b32_e32 v226, 3, v0
	v_and_b32_e32 v226, 56, v226
	v_or_b32_e32 v226, s3, v226
	v_lshlrev_b32_e32 v226, 2, v226
	v_mov_b32_e32 v227, 0
	v_lshl_add_u64 v[224:225], v[224:225], 0, v[226:227]
	global_load_dwordx4 v[228:231], v[224:225], off nt
	global_load_dwordx4 v[232:235], v[224:225], off offset:16 nt
	s_waitcnt vmcnt(17)
	ds_write_b128 v2, v[80:83]
	s_waitcnt vmcnt(16)
	ds_write_b128 v2, v[92:95] offset:5120
	s_waitcnt vmcnt(15)
	ds_write_b128 v2, v[96:99] offset:1280
	s_waitcnt vmcnt(14)
	ds_write_b128 v2, v[104:107] offset:6400
	s_waitcnt vmcnt(13)
	ds_write_b128 v2, v[108:111] offset:2560
	s_waitcnt vmcnt(12)
	ds_write_b128 v2, v[112:115] offset:7680
	s_waitcnt vmcnt(11)
	ds_write_b128 v2, v[116:119] offset:3840
	s_waitcnt vmcnt(10)
	ds_write_b128 v2, v[84:87] offset:8960
	v_mfma_f32_16x16x32_bf16 v[24:27], v[52:55], v[72:75], v[24:27]
	ds_read_b128 v[52:55], v145 offset:5120
	v_mfma_f32_16x16x32_bf16 v[32:35], v[56:59], v[72:75], v[32:35]
	ds_read_b128 v[56:59], v145 offset:6400
	ds_read_b128 v[72:75], v145
	ds_read_b128 v[80:83], v145 offset:1280
	ds_read_b128 v[84:87], v145 offset:7680
	ds_read_b128 v[92:95], v145 offset:8960
	s_waitcnt lgkmcnt(3)
	v_mfma_f32_16x16x32_bf16 v[20:23], v[52:55], v[72:75], v[20:23]
	v_mfma_f32_16x16x32_bf16 v[28:31], v[56:59], v[72:75], v[28:31]
	s_waitcnt lgkmcnt(1)
	v_mfma_f32_16x16x32_bf16 v[60:63], v[84:87], v[72:75], v[60:63]
	s_waitcnt lgkmcnt(0)
	v_mfma_f32_16x16x32_bf16 v[12:15], v[92:95], v[72:75], v[12:15]
	v_mfma_f32_16x16x32_bf16 v[44:47], v[52:55], v[80:83], v[44:47]
	v_mfma_f32_16x16x32_bf16 v[64:67], v[56:59], v[80:83], v[64:67]
	v_mfma_f32_16x16x32_bf16 v[68:71], v[84:87], v[80:83], v[68:71]
	v_mfma_f32_16x16x32_bf16 v[16:19], v[92:95], v[80:83], v[16:19]
	ds_read_b128 v[72:75], v145 offset:2560
	ds_read_b128 v[80:83], v145 offset:3840
	s_waitcnt vmcnt(9)
	ds_write_b128 v2, v[120:123]
	s_waitcnt vmcnt(8)
	ds_write_b128 v2, v[124:127] offset:5120
	s_waitcnt vmcnt(7)
	ds_write_b128 v2, v[36:39] offset:1280
	s_waitcnt vmcnt(6)
	ds_write_b128 v2, v[128:131] offset:6400
	s_waitcnt vmcnt(5)
	ds_write_b128 v2, v[132:135] offset:2560
	s_waitcnt vmcnt(4)
	ds_write_b128 v2, v[40:43] offset:7680
	s_waitcnt vmcnt(3)
	ds_write_b128 v2, v[136:139] offset:3840
	s_waitcnt vmcnt(2)
	ds_write_b128 v2, v[140:143] offset:8960
	s_waitcnt lgkmcnt(9)
	v_mfma_f32_16x16x32_bf16 v[76:79], v[52:55], v[72:75], v[76:79]
	ds_read_b128 v[36:39], v145 offset:5120
	v_mul_u32_u24_e32 v2, 0x110, v167
	v_add3_u32 v2, s4, v144, v2
	v_mfma_f32_16x16x32_bf16 v[88:91], v[56:59], v[72:75], v[88:91]
	v_mfma_f32_16x16x32_bf16 v[96:99], v[84:87], v[72:75], v[100:103]
	v_mfma_f32_16x16x32_bf16 v[48:51], v[92:95], v[72:75], v[48:51]
	s_waitcnt lgkmcnt(9)
	v_mfma_f32_16x16x32_bf16 v[4:7], v[52:55], v[80:83], v[4:7]
	v_mfma_f32_16x16x32_bf16 v[8:11], v[56:59], v[80:83], v[8:11]
	ds_read_b128 v[40:43], v145 offset:6400
	ds_read_b128 v[52:55], v145
	ds_read_b128 v[56:59], v145 offset:1280
	ds_read_b128 v[72:75], v145 offset:7680
	v_mfma_f32_16x16x32_bf16 v[24:27], v[84:87], v[80:83], v[24:27]
	v_mfma_f32_16x16x32_bf16 v[32:35], v[92:95], v[80:83], v[32:35]
	ds_read_b128 v[80:83], v145 offset:8960
	s_waitcnt lgkmcnt(3)
	v_mfma_f32_16x16x32_bf16 v[20:23], v[36:39], v[52:55], v[20:23]
	v_mfma_f32_16x16x32_bf16 v[28:31], v[40:43], v[52:55], v[28:31]
	s_waitcnt lgkmcnt(1)
	v_mfma_f32_16x16x32_bf16 v[60:63], v[72:75], v[52:55], v[60:63]
	s_waitcnt lgkmcnt(0)
	v_mfma_f32_16x16x32_bf16 v[12:15], v[80:83], v[52:55], v[12:15]
	v_mfma_f32_16x16x32_bf16 v[44:47], v[36:39], v[56:59], v[44:47]
	v_mfma_f32_16x16x32_bf16 v[52:55], v[40:43], v[56:59], v[64:67]
	v_mfma_f32_16x16x32_bf16 v[64:67], v[72:75], v[56:59], v[68:71]
	v_mfma_f32_16x16x32_bf16 v[16:19], v[80:83], v[56:59], v[16:19]
	ds_read_b128 v[56:59], v145 offset:2560
	s_nop 0
	ds_read_b128 v[68:71], v145 offset:3840
	s_waitcnt lgkmcnt(0)
	s_barrier
; #define LAS __attribute__((address_space(3)))
; #define STAMP(i) do { } while (0)
; template <int KSTEPS  >
; __device__ __forceinline__ void small_gemm_tile(Frame& F, const bf16* A, int lda, const bf16* Bt, int K, int r0, int c0, float (&v)[8]) {
;     ...
;     __syncthreads();
;     if (KSTEPS == 4) STAMP(26);
;     LAS float* part = (LAS float*)F.lds + wave * (64 * SG_LD);
; #pragma unroll
;     for (int a = 0; a < 4; ++a)
; #pragma unroll
;         for (int b = 0; b < 4; ++b) *(LAS f32x4v*)(part + (16 * a + fr) * SG_LD + 16 * b + 4 * fq) = acc[a][b];
;     __syncthreads();
;     { const int row = F.tid >> 3, cg8 = (F.tid & 7) * 8; const LAS float* p = (const LAS float*)F.lds + row * SG_LD + cg8;
;       f32x4v s0 = {0.f, 0.f, 0.f, 0.f}, s1 = {0.f, 0.f, 0.f, 0.f};
; #pragma unroll
;       for (int w = 0; w < 8; ++w) { s0 += *(const LAS f32x4v*)(p + w * (64 * SG_LD)); s1 += *(const LAS f32x4v*)(p + w * (64 * SG_LD) + 4); }
;       v[0] = s0[0]; v[1] = s0[1]; v[2] = s0[2]; v[3] = s0[3]; v[4] = s1[0]; v[5] = s1[1]; v[6] = s1[2]; v[7] = s1[3]; }
;     __syncthreads();
; }
; __device__ __forceinline__ void outproj_sample_tile(Frame& F, int tile, float* SS1) {
;     const int rm = tile >> 4, cn = tile & 15; float v[8];
;     STAMP(24);
;     small_gemm_tile<4>(F, (const bf16*)(F.ws + WS_MIX), DM, (const bf16*)(F.ws + WS_WOUT), DM, MP + 64 * rm, 64 * cn, v);
;     STAMP(25);
;     const int row = MP + 64 * rm + (F.tid >> 3), col = 64 * cn + 8 * (F.tid & 7); const size_t off = (size_t)row * DM + col;
;     const float* xs = F.in[1] + (size_t)(row - MP) * DM + col; bf16* XN = (bf16*)(F.ws + WS_XN);
;     const f32x4v xa = *(const f32x4v*)xs, xb = *(const f32x4v*)(xs + 4);
;     const f32x4v x0 = {xa[0] + v[0], xa[1] + v[1], xa[2] + v[2], xa[3] + v[3]}, x1 = {xb[0] + v[4], xb[1] + v[5], xb[2] + v[6], xb[3] + v[7]};
;     v4u w; w.x = pk2(x0[0], x0[1]); w.y = pk2(x0[2], x0[3]); w.z = pk2(x1[0], x1[1]); w.w = pk2(x1[2], x1[3]);
;     *(v4u*)(XN + off) = w;
;     float ss = (x0[0] * x0[0] + x0[1] * x0[1]) + (x0[2] * x0[2] + x0[3] * x0[3]) + (x1[0] * x1[0] + x1[1] * x1[1]) + (x1[2] * x1[2] + x1[3] * x1[3]);
;     ss += __shfl_xor(ss, 1); ss += __shfl_xor(ss, 2); ss += __shfl_xor(ss, 4);
;     if ((F.tid & 7) == 0) __hip_atomic_fetch_add(SS1 + row, ss, __ATOMIC_RELAXED, __HIP_MEMORY_SCOPE_AGENT);
	v_mfma_f32_16x16x32_bf16 v[84:87], v[40:43], v[56:59], v[88:91]
	ds_write_b128 v2, v[20:23]
	ds_write_b128 v2, v[28:31] offset:64
	ds_write_b128 v2, v[60:63] offset:128
	ds_write_b128 v2, v[12:15] offset:192
	ds_write_b128 v2, v[44:47] offset:4352
	ds_write_b128 v2, v[52:55] offset:4416
	v_mfma_f32_16x16x32_bf16 v[4:7], v[36:39], v[68:71], v[4:7]
	v_mfma_f32_16x16x32_bf16 v[88:91], v[72:75], v[56:59], v[96:99]
	v_mfma_f32_16x16x32_bf16 v[8:11], v[40:43], v[68:71], v[8:11]
	v_mfma_f32_16x16x32_bf16 v[76:79], v[36:39], v[56:59], v[76:79]
	ds_write_b128 v2, v[64:67] offset:4480
	ds_write_b128 v2, v[16:19] offset:4544
	s_nop 5
	ds_write_b128 v2, v[76:79] offset:8704
	v_mfma_f32_16x16x32_bf16 v[20:23], v[80:83], v[56:59], v[48:51]
	ds_write_b128 v2, v[84:87] offset:8768
	ds_write_b128 v2, v[88:91] offset:8832
	s_nop 5
	ds_write_b128 v2, v[20:23] offset:8896
	v_mfma_f32_16x16x32_bf16 v[12:15], v[72:75], v[68:71], v[24:27]
	ds_write_b128 v2, v[4:7] offset:13056
	ds_write_b128 v2, v[8:11] offset:13120
	s_nop 5
	ds_write_b128 v2, v[12:15] offset:13184
	v_mfma_f32_16x16x32_bf16 v[4:7], v[80:83], v[68:71], v[32:35]
	v_or_b32_e32 v68, s1, v155
	v_ashrrev_i32_e32 v69, 31, v68
	v_lshlrev_b64 v[68:69], 12, v[68:69]
	v_lshl_add_u64 v[68:69], s[62:63], 0, v[68:69]
	s_nop 3
	ds_write_b128 v2, v[4:7] offset:13248
	v_lshlrev_b32_e32 v2, 3, v0
	v_and_b32_e32 v2, 56, v2
	v_mul_u32_u24_e32 v4, 0x110, v155
	v_lshlrev_b32_e32 v5, 2, v2
	v_or_b32_e32 v76, s3, v2
	v_add3_u32 v60, 0, v4, v5
	v_lshlrev_b32_e32 v2, 2, v76
	v_add_u32_e32 v36, 0x11000, v60
	v_add_u32_e32 v40, 0x11010, v60
	v_add_u32_e32 v44, 0x15400, v60
	v_add_u32_e32 v48, 0x15410, v60
	v_add_u32_e32 v52, 0x19800, v60
	v_add_u32_e32 v56, 0x19810, v60
	v_add_u32_e32 v61, 0x1dc00, v60
	v_add_u32_e32 v64, 0x1dc10, v60
	v_lshl_add_u64 v[72:73], v[68:69], 0, v[2:3]
	s_waitcnt lgkmcnt(0)
	s_barrier
	ds_read_b128 v[4:7], v60
	ds_read_b128 v[8:11], v60 offset:16
	ds_read_b128 v[12:15], v60 offset:17408
	ds_read_b128 v[16:19], v60 offset:17424
	ds_read_b128 v[20:23], v60 offset:34816
	ds_read_b128 v[24:27], v60 offset:34832
	ds_read_b128 v[28:31], v60 offset:52224
	ds_read_b128 v[32:35], v60 offset:52240
	ds_read_b128 v[36:39], v36
	ds_read_b128 v[40:43], v40
	ds_read_b128 v[44:47], v44
	ds_read_b128 v[48:51], v48
	ds_read_b128 v[52:55], v52
	ds_read_b128 v[56:59], v56
	ds_read_b128 v[60:63], v61
	ds_read_b128 v[64:67], v64
	s_waitcnt lgkmcnt(0)
	s_barrier
	s_waitcnt vmcnt(0)
	v_mov_b32_e32 v68, v228
	v_mov_b32_e32 v69, v229
	v_mov_b32_e32 v70, v230
	v_mov_b32_e32 v71, v231
	v_mov_b32_e32 v72, v232
	v_mov_b32_e32 v73, v233
	v_mov_b32_e32 v74, v234
	v_mov_b32_e32 v75, v235
	v_pk_add_f32 v[6:7], v[6:7], 0 op_sel_hi:[1,0]
	v_pk_add_f32 v[4:5], v[4:5], 0 op_sel_hi:[1,0]
	v_pk_add_f32 v[10:11], v[10:11], 0 op_sel_hi:[1,0]
	v_pk_add_f32 v[8:9], v[8:9], 0 op_sel_hi:[1,0]
	v_pk_add_f32 v[6:7], v[6:7], v[14:15]
	v_pk_add_f32 v[4:5], v[4:5], v[12:13]
	v_pk_add_f32 v[10:11], v[10:11], v[18:19]
	v_pk_add_f32 v[8:9], v[8:9], v[16:17]
	v_pk_add_f32 v[6:7], v[6:7], v[22:23]
	v_pk_add_f32 v[4:5], v[4:5], v[20:21]
	v_pk_add_f32 v[10:11], v[10:11], v[26:27]
	v_pk_add_f32 v[8:9], v[8:9], v[24:25]
	v_pk_add_f32 v[6:7], v[6:7], v[30:31]
	v_pk_add_f32 v[4:5], v[4:5], v[28:29]
	v_pk_add_f32 v[10:11], v[10:11], v[34:35]
	v_pk_add_f32 v[8:9], v[8:9], v[32:33]
	v_pk_add_f32 v[6:7], v[6:7], v[38:39]
	v_pk_add_f32 v[4:5], v[4:5], v[36:37]
	v_pk_add_f32 v[10:11], v[10:11], v[42:43]
	v_pk_add_f32 v[8:9], v[8:9], v[40:41]
	v_pk_add_f32 v[6:7], v[6:7], v[46:47]
	v_pk_add_f32 v[4:5], v[4:5], v[44:45]
	v_pk_add_f32 v[10:11], v[10:11], v[50:51]
	v_pk_add_f32 v[8:9], v[8:9], v[48:49]
	v_pk_add_f32 v[6:7], v[6:7], v[54:55]
	v_pk_add_f32 v[4:5], v[4:5], v[52:53]
	v_pk_add_f32 v[10:11], v[10:11], v[58:59]
	v_pk_add_f32 v[8:9], v[8:9], v[56:57]
	v_pk_add_f32 v[6:7], v[6:7], v[62:63]
	v_pk_add_f32 v[12:13], v[4:5], v[60:61]
	v_pk_add_f32 v[10:11], v[10:11], v[66:67]
	v_pk_add_f32 v[8:9], v[8:9], v[64:65]
	v_or_b32_e32 v4, s0, v155
	s_waitcnt vmcnt(1)
	v_pk_add_f32 v[6:7], v[6:7], v[70:71]
	v_pk_add_f32 v[12:13], v[12:13], v[68:69]
	s_waitcnt vmcnt(0)
	v_pk_add_f32 v[14:15], v[10:11], v[74:75]
	v_pk_add_f32 v[10:11], v[8:9], v[72:73]
	v_pk_mul_f32 v[8:9], v[6:7], v[6:7]
	v_pk_mul_f32 v[16:17], v[12:13], v[12:13]
	v_pk_mul_f32 v[20:21], v[10:11], v[10:11]
	v_add_f32_e32 v5, v8, v9
	v_add_f32_e32 v8, v16, v17
	v_pk_mul_f32 v[18:19], v[14:15], v[14:15]
	v_add_f32_e32 v5, v8, v5
	v_add_f32_e32 v8, v20, v21
	v_add_f32_e32 v2, v18, v19
	v_add_f32_e32 v5, v5, v8
	v_add_f32_e32 v2, v2, v5
	v_mbcnt_lo_u32_b32 v5, -1, 0
	v_mbcnt_hi_u32_b32 v16, -1, v5
	v_and_b32_e32 v8, 64, v16
	v_xor_b32_e32 v5, 1, v16
	v_add_u32_e32 v17, 64, v8
	v_cmp_lt_i32_e32 vcc, v5, v17
	v_cvt_pk_bf16_f32 v9, v6, v7
	v_cvt_pk_bf16_f32 v8, v12, v13
	v_cndmask_b32_e32 v5, v16, v5, vcc
	v_lshlrev_b32_e32 v5, 2, v5
	ds_bpermute_b32 v18, v5, v2
	v_ashrrev_i32_e32 v5, 31, v4
	v_lshlrev_b64 v[6:7], 11, v[4:5]
	v_lshl_add_u64 v[12:13], s[46:47], 0, v[6:7]
	v_xor_b32_e32 v7, 4, v16
	s_waitcnt lgkmcnt(0)
	v_add_f32_e32 v18, v2, v18
	v_xor_b32_e32 v2, 2, v16
	v_cmp_lt_i32_e32 vcc, v2, v17
	v_cvt_pk_bf16_f32 v10, v10, v11
	v_cvt_pk_bf16_f32 v11, v14, v15
	v_cndmask_b32_e32 v2, v16, v2, vcc
	v_lshlrev_b32_e32 v2, 2, v2
	ds_bpermute_b32 v19, v2, v18
	v_cmp_lt_i32_e32 vcc, v7, v17
	v_lshlrev_b32_e32 v2, 1, v76
	v_lshl_add_u64 v[2:3], v[12:13], 0, v[2:3]
	v_cndmask_b32_e32 v7, v16, v7, vcc
	s_waitcnt lgkmcnt(0)
	v_add_f32_e32 v6, v18, v19
	v_lshlrev_b32_e32 v7, 2, v7
	ds_bpermute_b32 v7, v7, v6
	global_store_dwordx4 v[2:3], v[8:11], off
	v_and_b32_e32 v2, 7, v0
	v_cmp_eq_u32_e32 vcc, 0, v2
	s_and_saveexec_b64 s[0:1], vcc
	s_cbranch_execz .LBB0_763
	s_waitcnt lgkmcnt(0)
	v_add_f32_e32 v6, v6, v7
	v_lshl_add_u64 v[2:3], v[4:5], 2, s[12:13]
	global_atomic_add_f32 v[2:3], v6, off

; #define LAS __attribute__((address_space(3)))
; template <int KSTEPS  >
; __device__ __forceinline__ void small_gemm_tile(Frame& F, const bf16* A, int lda, const bf16* Bt, int K, int r0, int c0, float (&v)[8]) {
;     ...
;     const bf16* ap = A + (size_t)(r0 + lr) * lda + wave * (KSTEPS * 32) + 8 * lp;
;     const bf16* bp = Bt + (size_t)(c0 + lr) * K + wave * (KSTEPS * 32) + 8 * lp;
;     LAS unsigned char* SWA = F.lds + wave * 10240; LAS unsigned char* SWB = SWA + 5120;
;     v4u ra[D][4], rb[D][4];
; #pragma unroll
;     for (int s = 0; s < D - 1; ++s)
; #pragma unroll
;         for (int i = 0; i < 4; ++i) { ra[s][i] = *(const v4u*)(ap + (size_t)(16 * i) * lda + 32 * s); rb[s][i] = *(const v4u*)(bp + (size_t)(16 * i) * K + 32 * s); }
; #pragma unroll
;     for (int s = 0; s < KSTEPS; ++s) {
;         if (s + D - 1 < KSTEPS) {
; #pragma unroll
;             for (int i = 0; i < 4; ++i) { ra[(s + D - 1) % D][i] = *(const v4u*)(ap + (size_t)(16 * i) * lda + 32 * (s + D - 1)); rb[(s + D - 1) % D][i] = *(const v4u*)(bp + (size_t)(16 * i) * K + 32 * (s + D - 1)); } }
; #pragma unroll
;         for (int i = 0; i < 4; ++i) { *(LAS v4u*)(SWA + (16 * i + lr) * 80 + lp * 16) = ra[s % D][i]; *(LAS v4u*)(SWB + (16 * i + lr) * 80 + lp * 16) = rb[s % D][i]; }
;         s16x8 af[4], bf[4];
; #pragma unroll
;         for (int i = 0; i < 4; ++i) { af[i] = *(const LAS s16x8*)(SWA + (16 * i + fr) * 80 + fq * 16); bf[i] = *(const LAS s16x8*)(SWB + (16 * i + fr) * 80 + fq * 16); }
; #pragma unroll
;         for (int a = 0; a < 4; ++a)
; #pragma unroll
;             for (int bb = 0; bb < 4; ++bb) acc[a][bb] = __builtin_amdgcn_mfma_f32_16x16x32_bf16(bf[bb], af[a], acc[a][bb], 0, 0, 0);
.LBB0_809:
	s_and_b32 s16, s3, 0xffffffc0
	s_add_i32 s15, s16, 0x4000
	v_or_b32_e32 v8, s15, v13
	v_ashrrev_i32_e32 v9, 31, v8
	s_and_b32 s17, s5, 0x3c0
	v_lshlrev_b64 v[8:9], 11, v[8:9]
	v_lshl_add_u64 v[8:9], v[4:5], 0, v[8:9]
	v_or_b32_e32 v2, s17, v13
	v_lshlrev_b32_e32 v2, 11, v2
	v_add_co_u32_e64 v156, s[0:1], s7, v8
	v_lshl_add_u64 v[152:153], v[6:7], 0, v[2:3]
	s_nop 0
	v_addc_co_u32_e64 v157, s[0:1], 0, v9, s[0:1]
	v_add_co_u32_e64 v160, s[0:1], s7, v152
	s_waitcnt lgkmcnt(0)
	global_load_dwordx4 v[28:31], v[8:9], off
	global_load_dwordx4 v[32:35], v[152:153], off
	v_addc_co_u32_e64 v161, s[0:1], 0, v153, s[0:1]
	v_add_co_u32_e64 v164, s[0:1], s8, v8
	global_load_dwordx4 v[36:39], v[156:157], off
	global_load_dwordx4 v[40:43], v[160:161], off
	v_addc_co_u32_e64 v165, s[0:1], 0, v9, s[0:1]
	v_add_co_u32_e64 v166, s[0:1], s8, v152
	global_load_dwordx4 v[44:47], v[164:165], off
	s_nop 0
	v_addc_co_u32_e64 v167, s[0:1], 0, v153, s[0:1]
	v_add_co_u32_e64 v172, s[0:1], s9, v152
	global_load_dwordx4 v[48:51], v[166:167], off
	s_nop 0
	v_addc_co_u32_e64 v173, s[0:1], 0, v153, s[0:1]
	v_add_co_u32_e64 v168, s[0:1], s9, v8
	global_load_dwordx4 v[52:55], v[172:173], off
	s_nop 0
	v_addc_co_u32_e64 v169, s[0:1], 0, v9, s[0:1]
	global_load_dwordx4 v[56:59], v[168:169], off
	global_load_dwordx4 v[60:63], v[8:9], off offset:64
	global_load_dwordx4 v[64:67], v[152:153], off offset:64
	global_load_dwordx4 v[68:71], v[156:157], off offset:64
	global_load_dwordx4 v[72:75], v[160:161], off offset:64
	global_load_dwordx4 v[76:79], v[164:165], off offset:64
	global_load_dwordx4 v[80:83], v[166:167], off offset:64
	global_load_dwordx4 v[84:87], v[168:169], off offset:64
	global_load_dwordx4 v[88:91], v[172:173], off offset:64
	s_waitcnt vmcnt(14)
	ds_write_b128 v24, v[32:35] offset:5120
	s_waitcnt vmcnt(12)
	ds_write_b128 v24, v[40:43] offset:6400
	s_waitcnt vmcnt(10)
	ds_write_b128 v24, v[48:51] offset:7680
	s_waitcnt vmcnt(9)
	ds_write_b128 v24, v[52:55] offset:8960
	ds_write_b128 v24, v[28:31]
	ds_write_b128 v24, v[36:39] offset:1280
	ds_write_b128 v24, v[44:47] offset:2560
	s_waitcnt vmcnt(8)
	ds_write_b128 v24, v[56:59] offset:3840
	ds_read_b128 v[28:31], v25 offset:5120
	ds_read_b128 v[32:35], v25 offset:6400
	ds_read_b128 v[36:39], v25
	ds_read_b128 v[40:43], v25 offset:1280
	ds_read_b128 v[48:51], v25 offset:7680
	ds_read_b128 v[56:59], v25 offset:8960
	ds_read_b128 v[108:111], v25 offset:2560
	ds_read_b128 v[112:115], v25 offset:3840
	s_waitcnt vmcnt(7)
	ds_write_b128 v24, v[60:63]
	s_waitcnt vmcnt(6)
	ds_write_b128 v24, v[64:67] offset:5120
	s_waitcnt vmcnt(5)
	ds_write_b128 v24, v[68:71] offset:1280
	s_waitcnt vmcnt(4)
	ds_write_b128 v24, v[72:75] offset:6400
	s_waitcnt vmcnt(3)
	ds_write_b128 v24, v[76:79] offset:2560
	s_waitcnt vmcnt(2)
	ds_write_b128 v24, v[80:83] offset:7680
	s_waitcnt vmcnt(1)
	ds_write_b128 v24, v[84:87] offset:3840
	s_waitcnt vmcnt(0)
	ds_write_b128 v24, v[88:91] offset:8960
	ds_read_b128 v[60:63], v25 offset:5120
	ds_read_b128 v[64:67], v25 offset:6400
	ds_read_b128 v[68:71], v25
	ds_read_b128 v[72:75], v25 offset:1280
	ds_read_b128 v[76:79], v25 offset:7680
	ds_read_b128 v[80:83], v25 offset:8960
	s_waitcnt lgkmcnt(14)
	v_mfma_f32_16x16x32_bf16 v[44:47], v[28:31], v[36:39], 0
	v_mfma_f32_16x16x32_bf16 v[52:55], v[32:35], v[36:39], 0
	v_mfma_f32_16x16x32_bf16 v[92:95], v[48:51], v[36:39], 0
	v_mfma_f32_16x16x32_bf16 v[36:39], v[56:59], v[36:39], 0
	v_mfma_f32_16x16x32_bf16 v[96:99], v[28:31], v[40:43], 0
	v_mfma_f32_16x16x32_bf16 v[100:103], v[32:35], v[40:43], 0
	v_mfma_f32_16x16x32_bf16 v[104:107], v[48:51], v[40:43], 0
	v_mfma_f32_16x16x32_bf16 v[40:43], v[56:59], v[40:43], 0
	s_waitcnt lgkmcnt(3)
	v_mfma_f32_16x16x32_bf16 v[44:47], v[60:63], v[68:71], v[44:47]
	v_mfma_f32_16x16x32_bf16 v[52:55], v[64:67], v[68:71], v[52:55]
	s_waitcnt lgkmcnt(1)
	v_mfma_f32_16x16x32_bf16 v[84:87], v[76:79], v[68:71], v[92:95]
	s_waitcnt lgkmcnt(0)
	v_mfma_f32_16x16x32_bf16 v[36:39], v[80:83], v[68:71], v[36:39]
	v_mfma_f32_16x16x32_bf16 v[68:71], v[60:63], v[72:75], v[96:99]
	v_mfma_f32_16x16x32_bf16 v[88:91], v[64:67], v[72:75], v[100:103]
	s_nop 1
	global_load_dwordx4 v[96:99], v[8:9], off offset:128
	v_mfma_f32_16x16x32_bf16 v[92:95], v[76:79], v[72:75], v[104:107]
	ds_read_b128 v[100:103], v25 offset:3840
	v_mfma_f32_16x16x32_bf16 v[40:43], v[80:83], v[72:75], v[40:43]
	ds_read_b128 v[72:75], v25 offset:2560
	v_mfma_f32_16x16x32_bf16 v[116:119], v[28:31], v[108:111], 0
	v_mfma_f32_16x16x32_bf16 v[120:123], v[32:35], v[108:111], 0
	v_mfma_f32_16x16x32_bf16 v[124:127], v[48:51], v[108:111], 0
	v_mfma_f32_16x16x32_bf16 v[108:111], v[56:59], v[108:111], 0
	v_mfma_f32_16x16x32_bf16 v[28:31], v[28:31], v[112:115], 0
	v_mfma_f32_16x16x32_bf16 v[32:35], v[32:35], v[112:115], 0
	v_mfma_f32_16x16x32_bf16 v[48:51], v[48:51], v[112:115], 0
	v_mfma_f32_16x16x32_bf16 v[56:59], v[56:59], v[112:115], 0
	s_waitcnt lgkmcnt(0)
; #define LAS __attribute__((address_space(3)))
; template <int KSTEPS  >
; __device__ __forceinline__ void small_gemm_tile(Frame& F, const bf16* A, int lda, const bf16* Bt, int K, int r0, int c0, float (&v)[8]) {
;     ...
;     for (int s = 0; s < KSTEPS; ++s) {
;         if (s + D - 1 < KSTEPS) {
; #pragma unroll
;             for (int i = 0; i < 4; ++i) { ra[(s + D - 1) % D][i] = *(const v4u*)(ap + (size_t)(16 * i) * lda + 32 * (s + D - 1)); rb[(s + D - 1) % D][i] = *(const v4u*)(bp + (size_t)(16 * i) * K + 32 * (s + D - 1)); } }
; #pragma unroll
;         for (int i = 0; i < 4; ++i) { *(LAS v4u*)(SWA + (16 * i + lr) * 80 + lp * 16) = ra[s % D][i]; *(LAS v4u*)(SWB + (16 * i + lr) * 80 + lp * 16) = rb[s % D][i]; }
;         s16x8 af[4], bf[4];
; #pragma unroll
;         for (int i = 0; i < 4; ++i) { af[i] = *(const LAS s16x8*)(SWA + (16 * i + fr) * 80 + fq * 16); bf[i] = *(const LAS s16x8*)(SWB + (16 * i + fr) * 80 + fq * 16); }
; #pragma unroll
;         for (int a = 0; a < 4; ++a)
; #pragma unroll
;             for (int bb = 0; bb < 4; ++bb) acc[a][bb] = __builtin_amdgcn_mfma_f32_16x16x32_bf16(bf[bb], af[a], acc[a][bb], 0, 0, 0);
;     }
; __device__ __forceinline__ void outproj_sample_tile(Frame& F, int tile, float* SS1) {
;     ...
;     const float* xs = F.in[1] + (size_t)(row - MP) * DM + col; bf16* XN = (bf16*)(F.ws + WS_XN);
;     const f32x4v xa = *(const f32x4v*)xs, xb = *(const f32x4v*)(xs + 4);
	v_mfma_f32_16x16x32_bf16 v[104:107], v[60:63], v[72:75], v[116:119]
	global_load_dwordx4 v[112:115], v[152:153], off offset:128
	s_nop 1
	global_load_dwordx4 v[116:119], v[156:157], off offset:128
	global_load_dwordx4 v[128:131], v[160:161], off offset:128
	global_load_dwordx4 v[132:135], v[164:165], off offset:128
	global_load_dwordx4 v[136:139], v[166:167], off offset:128
	global_load_dwordx4 v[140:143], v[168:169], off offset:128
	global_load_dwordx4 v[144:147], v[172:173], off offset:128
	global_load_dwordx4 v[148:151], v[8:9], off offset:192
	v_mfma_f32_16x16x32_bf16 v[120:123], v[64:67], v[72:75], v[120:123]
	v_add_u32_e32 v8, s16, v155
	v_ashrrev_i32_e32 v9, 31, v8
	v_lshlrev_b64 v[8:9], 12, v[8:9]
	v_mfma_f32_16x16x32_bf16 v[124:127], v[76:79], v[72:75], v[124:127]
	v_mfma_f32_16x16x32_bf16 v[72:75], v[80:83], v[72:75], v[108:111]
	s_nop 2
	global_load_dwordx4 v[108:111], v[152:153], off offset:192
	s_nop 0
	global_load_dwordx4 v[156:159], v[156:157], off offset:192
	s_nop 0
	global_load_dwordx4 v[160:163], v[160:161], off offset:192
	v_mfma_f32_16x16x32_bf16 v[28:31], v[60:63], v[100:103], v[28:31]
	global_load_dwordx4 v[60:63], v[164:165], off offset:192
	s_nop 0
	global_load_dwordx4 v[164:167], v[166:167], off offset:192
	s_nop 0
	global_load_dwordx4 v[168:171], v[168:169], off offset:192
	v_mfma_f32_16x16x32_bf16 v[32:35], v[64:67], v[100:103], v[32:35]
	global_load_dwordx4 v[64:67], v[172:173], off offset:192
	v_readlane_b32 s18, v238, 6
	v_readlane_b32 s19, v238, 7
	v_lshrrev_b32_e32 v224, 3, v0
	v_add_u32_e32 v224, s16, v224
	v_mov_b32_e32 v225, 0
	v_lshlrev_b64 v[224:225], 12, v[224:225]
	v_lshl_add_u64 v[224:225], s[18:19], 0, v[224:225]
	v_lshlrev_b32_e32 v226, 3, v0
	v_and_b32_e32 v226, 56, v226
	v_or_b32_e32 v226, s17, v226
	v_lshlrev_b32_e32 v226, 2, v226
	v_mov_b32_e32 v227, 0
	v_lshl_add_u64 v[224:225], v[224:225], 0, v[226:227]
	global_load_dwordx4 v[228:231], v[224:225], off nt
	global_load_dwordx4 v[232:235], v[224:225], off offset:16 nt
	s_waitcnt vmcnt(17)
	ds_write_b128 v24, v[96:99]
	s_waitcnt vmcnt(16)
	ds_write_b128 v24, v[112:115] offset:5120
	s_waitcnt vmcnt(15)
	ds_write_b128 v24, v[116:119] offset:1280
	s_waitcnt vmcnt(14)
	ds_write_b128 v24, v[128:131] offset:6400
	s_waitcnt vmcnt(13)
	ds_write_b128 v24, v[132:135] offset:2560
	s_waitcnt vmcnt(12)
	ds_write_b128 v24, v[136:139] offset:7680
	s_waitcnt vmcnt(11)
	ds_write_b128 v24, v[140:143] offset:3840
	s_waitcnt vmcnt(10)
	ds_write_b128 v24, v[144:147] offset:8960
	v_mfma_f32_16x16x32_bf16 v[48:51], v[76:79], v[100:103], v[48:51]
	ds_read_b128 v[76:79], v25 offset:5120
	v_mfma_f32_16x16x32_bf16 v[56:59], v[80:83], v[100:103], v[56:59]
	ds_read_b128 v[80:83], v25 offset:6400
	ds_read_b128 v[96:99], v25
	ds_read_b128 v[100:103], v25 offset:1280
	ds_read_b128 v[112:115], v25 offset:7680
	ds_read_b128 v[116:119], v25 offset:8960
	s_waitcnt lgkmcnt(3)
	v_mfma_f32_16x16x32_bf16 v[44:47], v[76:79], v[96:99], v[44:47]
	v_mfma_f32_16x16x32_bf16 v[52:55], v[80:83], v[96:99], v[52:55]
	s_waitcnt lgkmcnt(1)
	v_mfma_f32_16x16x32_bf16 v[84:87], v[112:115], v[96:99], v[84:87]
	s_waitcnt lgkmcnt(0)
	v_mfma_f32_16x16x32_bf16 v[36:39], v[116:119], v[96:99], v[36:39]
	v_mfma_f32_16x16x32_bf16 v[68:71], v[76:79], v[100:103], v[68:71]
	v_mfma_f32_16x16x32_bf16 v[88:91], v[80:83], v[100:103], v[88:91]
	v_mfma_f32_16x16x32_bf16 v[92:95], v[112:115], v[100:103], v[92:95]
	v_mfma_f32_16x16x32_bf16 v[40:43], v[116:119], v[100:103], v[40:43]
	ds_read_b128 v[96:99], v25 offset:2560
	ds_read_b128 v[100:103], v25 offset:3840
	s_waitcnt vmcnt(9)
	ds_write_b128 v24, v[148:151]
	s_waitcnt vmcnt(8)
	ds_write_b128 v24, v[108:111] offset:5120
	s_waitcnt vmcnt(7)
	ds_write_b128 v24, v[156:159] offset:1280
	s_waitcnt vmcnt(6)
	ds_write_b128 v24, v[160:163] offset:6400
	s_waitcnt vmcnt(5)
	ds_write_b128 v24, v[60:63] offset:2560
	s_waitcnt vmcnt(4)
	ds_write_b128 v24, v[164:167] offset:7680
	s_waitcnt vmcnt(3)
	ds_write_b128 v24, v[168:171] offset:3840
	s_waitcnt vmcnt(2)
	ds_write_b128 v24, v[64:67] offset:8960
	s_waitcnt lgkmcnt(9)
	v_mfma_f32_16x16x32_bf16 v[104:107], v[76:79], v[96:99], v[104:107]
	ds_read_b128 v[60:63], v25 offset:5120
	ds_read_b128 v[64:67], v25 offset:6400
	v_mfma_f32_16x16x32_bf16 v[120:123], v[80:83], v[96:99], v[120:123]
	v_mfma_f32_16x16x32_bf16 v[124:127], v[112:115], v[96:99], v[124:127]
	v_mfma_f32_16x16x32_bf16 v[72:75], v[116:119], v[96:99], v[72:75]
	s_waitcnt lgkmcnt(10)
	v_mfma_f32_16x16x32_bf16 v[28:31], v[76:79], v[100:103], v[28:31]
	v_mfma_f32_16x16x32_bf16 v[32:35], v[80:83], v[100:103], v[32:35]
	ds_read_b128 v[76:79], v25
	ds_read_b128 v[80:83], v25 offset:1280
	ds_read_b128 v[96:99], v25 offset:7680
	v_mfma_f32_16x16x32_bf16 v[48:51], v[112:115], v[100:103], v[48:51]
	v_mfma_f32_16x16x32_bf16 v[56:59], v[116:119], v[100:103], v[56:59]
	ds_read_b128 v[100:103], v25 offset:8960
	s_waitcnt lgkmcnt(3)
	v_mfma_f32_16x16x32_bf16 v[44:47], v[60:63], v[76:79], v[44:47]
	v_mfma_f32_16x16x32_bf16 v[52:55], v[64:67], v[76:79], v[52:55]
	s_waitcnt lgkmcnt(1)
	v_mfma_f32_16x16x32_bf16 v[84:87], v[96:99], v[76:79], v[84:87]
	s_waitcnt lgkmcnt(0)
	v_mfma_f32_16x16x32_bf16 v[36:39], v[100:103], v[76:79], v[36:39]
	v_mfma_f32_16x16x32_bf16 v[68:71], v[60:63], v[80:83], v[68:71]
	v_mfma_f32_16x16x32_bf16 v[76:79], v[64:67], v[80:83], v[88:91]
	v_mfma_f32_16x16x32_bf16 v[88:91], v[96:99], v[80:83], v[92:95]
	v_mfma_f32_16x16x32_bf16 v[40:43], v[100:103], v[80:83], v[40:43]
	ds_read_b128 v[80:83], v25 offset:2560
	s_nop 0
	ds_read_b128 v[92:95], v25 offset:3840
	s_waitcnt lgkmcnt(0)
	s_barrier
; #define LAS __attribute__((address_space(3)))
; #define STAMP(i) do { } while (0)
; template <int KSTEPS  >
; __device__ __forceinline__ void small_gemm_tile(Frame& F, const bf16* A, int lda, const bf16* Bt, int K, int r0, int c0, float (&v)[8]) {
;     ...
;     __syncthreads();
;     if (KSTEPS == 4) STAMP(26);
;     LAS float* part = (LAS float*)F.lds + wave * (64 * SG_LD);
; #pragma unroll
;     for (int a = 0; a < 4; ++a)
; #pragma unroll
;         for (int b = 0; b < 4; ++b) *(LAS f32x4v*)(part + (16 * a + fr) * SG_LD + 16 * b + 4 * fq) = acc[a][b];
;     __syncthreads();
;     { const int row = F.tid >> 3, cg8 = (F.tid & 7) * 8; const LAS float* p = (const LAS float*)F.lds + row * SG_LD + cg8;
;       f32x4v s0 = {0.f, 0.f, 0.f, 0.f}, s1 = {0.f, 0.f, 0.f, 0.f};
; #pragma unroll
;       for (int w = 0; w < 8; ++w) { s0 += *(const LAS f32x4v*)(p + w * (64 * SG_LD)); s1 += *(const LAS f32x4v*)(p + w * (64 * SG_LD) + 4); }
;       v[0] = s0[0]; v[1] = s0[1]; v[2] = s0[2]; v[3] = s0[3]; v[4] = s1[0]; v[5] = s1[1]; v[6] = s1[2]; v[7] = s1[3]; }
;     __syncthreads();
; }
; __device__ __forceinline__ void outproj_sample_tile(Frame& F, int tile, float* SS1) {
;     const int rm = tile >> 4, cn = tile & 15; float v[8];
;     STAMP(24);
;     small_gemm_tile<4>(F, (const bf16*)(F.ws + WS_MIX), DM, (const bf16*)(F.ws + WS_WOUT), DM, MP + 64 * rm, 64 * cn, v);
;     STAMP(25);
;     const int row = MP + 64 * rm + (F.tid >> 3), col = 64 * cn + 8 * (F.tid & 7); const size_t off = (size_t)row * DM + col;
;     const float* xs = F.in[1] + (size_t)(row - MP) * DM + col; bf16* XN = (bf16*)(F.ws + WS_XN);
;     const f32x4v xa = *(const f32x4v*)xs, xb = *(const f32x4v*)(xs + 4);
;     const f32x4v x0 = {xa[0] + v[0], xa[1] + v[1], xa[2] + v[2], xa[3] + v[3]}, x1 = {xb[0] + v[4], xb[1] + v[5], xb[2] + v[6], xb[3] + v[7]};
;     v4u w; w.x = pk2(x0[0], x0[1]); w.y = pk2(x0[2], x0[3]); w.z = pk2(x1[0], x1[1]); w.w = pk2(x1[2], x1[3]);
;     *(v4u*)(XN + off) = w;
;     float ss = (x0[0] * x0[0] + x0[1] * x0[1]) + (x0[2] * x0[2] + x0[3] * x0[3]) + (x1[0] * x1[0] + x1[1] * x1[1]) + (x1[2] * x1[2] + x1[3] * x1[3]);
;     ss += __shfl_xor(ss, 1); ss += __shfl_xor(ss, 2); ss += __shfl_xor(ss, 4);
;     if ((F.tid & 7) == 0) __hip_atomic_fetch_add(SS1 + row, ss, __ATOMIC_RELAXED, __HIP_MEMORY_SCOPE_AGENT);
	v_mfma_f32_16x16x32_bf16 v[108:111], v[64:67], v[80:83], v[120:123]
	ds_write_b128 v26, v[44:47]
	ds_write_b128 v26, v[52:55] offset:64
	ds_write_b128 v26, v[84:87] offset:128
	ds_write_b128 v26, v[36:39] offset:192
	ds_write_b128 v26, v[68:71] offset:4352
	ds_write_b128 v26, v[76:79] offset:4416
	v_mfma_f32_16x16x32_bf16 v[28:31], v[60:63], v[92:95], v[28:31]
	v_mfma_f32_16x16x32_bf16 v[112:115], v[96:99], v[80:83], v[124:127]
	v_mfma_f32_16x16x32_bf16 v[32:35], v[64:67], v[92:95], v[32:35]
	v_mfma_f32_16x16x32_bf16 v[104:107], v[60:63], v[80:83], v[104:107]
	ds_write_b128 v26, v[88:91] offset:4480
	ds_write_b128 v26, v[40:43] offset:4544
	s_nop 5
	ds_write_b128 v26, v[104:107] offset:8704
	v_mfma_f32_16x16x32_bf16 v[44:47], v[100:103], v[80:83], v[72:75]
	ds_write_b128 v26, v[108:111] offset:8768
	ds_write_b128 v26, v[112:115] offset:8832
	s_nop 5
	ds_write_b128 v26, v[44:47] offset:8896
	v_mfma_f32_16x16x32_bf16 v[36:39], v[96:99], v[92:95], v[48:51]
	ds_write_b128 v26, v[28:31] offset:13056
	ds_write_b128 v26, v[32:35] offset:13120
	s_nop 5
	ds_write_b128 v26, v[36:39] offset:13184
	v_mfma_f32_16x16x32_bf16 v[28:31], v[100:103], v[92:95], v[56:59]
	v_or_b32_e32 v100, s17, v14
	v_readlane_b32 s16, v238, 4
	v_readlane_b32 s18, v238, 6
	v_readlane_b32 s19, v238, 7
	v_lshlrev_b32_e32 v2, 2, v100
	s_nop 2
	ds_write_b128 v26, v[28:31] offset:13248
	v_lshl_add_u64 v[8:9], s[18:19], 0, v[8:9]
	v_lshl_add_u64 v[8:9], v[8:9], 0, v[2:3]
	s_waitcnt lgkmcnt(0)
	s_barrier
	ds_read_b128 v[28:31], v15
	ds_read_b128 v[32:35], v15 offset:16
	ds_read_b128 v[36:39], v15 offset:17408
	ds_read_b128 v[40:43], v15 offset:17424
	ds_read_b128 v[44:47], v15 offset:34816
	ds_read_b128 v[48:51], v15 offset:34832
	ds_read_b128 v[52:55], v15 offset:52224
	ds_read_b128 v[56:59], v15 offset:52240
	ds_read_b128 v[60:63], v16
	ds_read_b128 v[64:67], v17
	ds_read_b128 v[68:71], v18
	ds_read_b128 v[72:75], v19
	ds_read_b128 v[76:79], v20
	ds_read_b128 v[80:83], v21
	ds_read_b128 v[84:87], v22
	ds_read_b128 v[88:91], v23
	s_waitcnt lgkmcnt(0)
	s_barrier
	s_waitcnt vmcnt(0)
	v_mov_b32_e32 v92, v228
	v_mov_b32_e32 v93, v229
	v_mov_b32_e32 v94, v230
	v_mov_b32_e32 v95, v231
	v_mov_b32_e32 v96, v232
	v_mov_b32_e32 v97, v233
	v_mov_b32_e32 v98, v234
	v_mov_b32_e32 v99, v235
	v_pk_add_f32 v[8:9], v[30:31], 0 op_sel_hi:[1,0]
	v_pk_add_f32 v[28:29], v[28:29], 0 op_sel_hi:[1,0]
	v_pk_add_f32 v[30:31], v[34:35], 0 op_sel_hi:[1,0]
	v_pk_add_f32 v[32:33], v[32:33], 0 op_sel_hi:[1,0]
	v_pk_add_f32 v[8:9], v[8:9], v[38:39]
	v_pk_add_f32 v[28:29], v[28:29], v[36:37]
	v_pk_add_f32 v[30:31], v[30:31], v[42:43]
	v_pk_add_f32 v[32:33], v[32:33], v[40:41]
	v_pk_add_f32 v[8:9], v[8:9], v[46:47]
	v_pk_add_f32 v[28:29], v[28:29], v[44:45]
	v_pk_add_f32 v[30:31], v[30:31], v[50:51]
	v_pk_add_f32 v[32:33], v[32:33], v[48:49]
	v_pk_add_f32 v[8:9], v[8:9], v[54:55]
	v_pk_add_f32 v[28:29], v[28:29], v[52:53]
	v_pk_add_f32 v[30:31], v[30:31], v[58:59]
	v_pk_add_f32 v[32:33], v[32:33], v[56:57]
	v_pk_add_f32 v[8:9], v[8:9], v[62:63]
	v_pk_add_f32 v[28:29], v[28:29], v[60:61]
	v_pk_add_f32 v[30:31], v[30:31], v[66:67]
	v_pk_add_f32 v[32:33], v[32:33], v[64:65]
	v_pk_add_f32 v[8:9], v[8:9], v[70:71]
	v_pk_add_f32 v[28:29], v[28:29], v[68:69]
	v_pk_add_f32 v[30:31], v[30:31], v[74:75]
	v_pk_add_f32 v[32:33], v[32:33], v[72:73]
	v_pk_add_f32 v[8:9], v[8:9], v[78:79]
	v_pk_add_f32 v[28:29], v[28:29], v[76:77]
	v_pk_add_f32 v[30:31], v[30:31], v[82:83]
	v_pk_add_f32 v[32:33], v[32:33], v[80:81]
	v_pk_add_f32 v[8:9], v[8:9], v[86:87]
	v_pk_add_f32 v[28:29], v[28:29], v[84:85]
	v_pk_add_f32 v[30:31], v[30:31], v[90:91]
	v_pk_add_f32 v[32:33], v[32:33], v[88:89]
	v_readlane_b32 s17, v238, 5
	v_readlane_b32 s20, v238, 8
	v_readlane_b32 s21, v238, 9
	v_readlane_b32 s22, v238, 10
	v_readlane_b32 s23, v238, 11
	v_readlane_b32 s24, v238, 12
	v_readlane_b32 s25, v238, 13
	v_readlane_b32 s26, v238, 14
	v_readlane_b32 s27, v238, 15
	v_readlane_b32 s28, v238, 16
	v_readlane_b32 s29, v238, 17
	v_readlane_b32 s30, v238, 18
	v_readlane_b32 s31, v238, 19
	s_waitcnt vmcnt(1)
	v_pk_add_f32 v[34:35], v[8:9], v[94:95]
	v_pk_add_f32 v[28:29], v[28:29], v[92:93]
	s_waitcnt vmcnt(0)
	v_pk_add_f32 v[36:37], v[30:31], v[98:99]
	v_pk_add_f32 v[32:33], v[32:33], v[96:97]
	v_pk_mul_f32 v[8:9], v[34:35], v[34:35]
	v_pk_mul_f32 v[30:31], v[28:29], v[28:29]
	v_pk_mul_f32 v[40:41], v[32:33], v[32:33]
	v_add_f32_e32 v8, v8, v9
	v_add_f32_e32 v9, v30, v31
	v_pk_mul_f32 v[38:39], v[36:37], v[36:37]
	v_add_f32_e32 v8, v9, v8
	v_add_f32_e32 v9, v40, v41
	v_add_f32_e32 v2, v38, v39
	v_add_f32_e32 v8, v8, v9
	v_add_f32_e32 v2, v2, v8
	ds_bpermute_b32 v27, v10, v2
	v_add_u32_e32 v8, s15, v155
	v_cvt_pk_bf16_f32 v30, v28, v29
	v_ashrrev_i32_e32 v9, 31, v8
	v_cvt_pk_bf16_f32 v31, v34, v35
	s_waitcnt lgkmcnt(0)
	v_add_f32_e32 v2, v2, v27
	ds_bpermute_b32 v27, v11, v2
	v_lshlrev_b64 v[34:35], 11, v[8:9]
	v_lshl_add_u64 v[34:35], s[46:47], 0, v[34:35]
	v_cvt_pk_bf16_f32 v32, v32, v33
	v_cvt_pk_bf16_f32 v33, v36, v37
	s_waitcnt lgkmcnt(0)
	v_add_f32_e32 v27, v2, v27
	ds_bpermute_b32 v28, v12, v27
	v_lshlrev_b32_e32 v2, 1, v100
	v_lshl_add_u64 v[34:35], v[34:35], 0, v[2:3]
	global_store_dwordx4 v[34:35], v[30:33], off
	s_and_saveexec_b64 s[0:1], vcc
	s_cbranch_execz .LBB0_808
	s_waitcnt lgkmcnt(0)
	v_add_f32_e32 v2, v27, v28
	v_lshl_add_u64 v[8:9], v[8:9], 2, s[12:13]
	global_atomic_add_f32 v[8:9], v2, off
	s_branch .LBB0_808
